# f28 + the compiler's conservative s_waitcnt vmcnt(0) at the top of the P1 bf16 K-loop removed (the counted vmcnt(8)+barrier protocol of the same loop template already orders the LDS ring)
# baseline (speedup 1.0000x reference)
; #define PG8_STAGE(bufoff, gbase, voff) do { _Pragma("unroll") for (int _i = 0; _i < 2; ++_i) \
;         __builtin_amdgcn_global_load_lds((const unsigned*)((const char*)(gbase) + (voff)[_i]), (LAS unsigned*)(lds + (bufoff) + ldsw + _i * 8192), 16, 0, 0); } while (0)
; #define PG8_LDA(dst, b, h) do { _Pragma("unroll") for (int m = 0; m < 4; ++m) _Pragma("unroll") for (int k = 0; k < 2; ++k) dst[m][k] = *(const LAS bf16x8*)(lds + PG8_SA(b, h) + aoff + m * 2048 + k * 1024); } while (0)
; #define PG8_LDB(dst, b, h) do { _Pragma("unroll") for (int n = 0; n < 2; ++n) _Pragma("unroll") for (int k = 0; k < 2; ++k) dst[n][k] = *(const LAS bf16x8*)(lds + PG8_SB(b, h) + boff + n * 2048 + k * 1024); } while (0)
; #define PG8_MMA(ai, bj, At, Bt) do { __builtin_amdgcn_s_setprio(1); _Pragma("unroll") for (int m = 0; m < 4; ++m) _Pragma("unroll") for (int n = 0; n < 2; ++n) _Pragma("unroll") for (int k = 0; k < 2; ++k) \
;         acc[ai][bj][m][n] = __builtin_amdgcn_mfma_f32_16x16x32_bf16(Bt[n][k], At[m][k], acc[ai][bj][m][n], 0, 0, 0); __builtin_amdgcn_s_setprio(0); } while (0)
; #define PG8_WAIT_V(n) asm volatile("s_waitcnt vmcnt(" #n ")" ::: "memory")
; #define PG8_WAIT_L(n) asm volatile("s_waitcnt lgkmcnt(" #n ")" ::: "memory")
; #define PG8_BAR __builtin_amdgcn_s_barrier()
; #define PG8_SCHED __builtin_amdgcn_sched_barrier(0)
; #define PG8_STAGE(bufoff, gbase, voff) do { _Pragma("unroll") for (int _i = 0; _i < 2; ++_i) \
;         __builtin_amdgcn_global_load_lds((const unsigned*)((const char*)(gbase) + (voff)[_i]), (LAS unsigned*)(lds + (bufoff) + ldsw + _i * 8192), 16, 0, 0); } while (0)
; #define PG8_BAR __builtin_amdgcn_s_barrier()
; template <class Epi, class Sched, bool ALIGN_EPI, bool SP2>
; __device__ __forceinline__ void gemm_phase(LAS unsigned char* lds, const int K, const Sched& S, const Epi& E) {
;     ...
;             if constexpr (SP2) {
;             PG8_LDB(B0, 0, 0); PG8_LDB(B1, 0, 1); PG8_SCHED; PG8_LDA(At, 0, 0); PG8_STAGE(PG8_SA(1, 1), a1 + hstep, voffA);
;             PG8_WAIT_V(8); PG8_WAIT_L(0); PG8_BAR; PG8_MMA(0, 0, At, B0); PG8_MMA(0, 1, At, B1); PG8_BAR; PG8_SCHED;
;             PG8_LDA(At, 0, 1); PG8_STAGE(PG8_SB(0, 0), b2, voffB); PG8_STAGE(PG8_SB(0, 1), b2 + hstep, voffB); PG8_STAGE(PG8_SA(0, 0), a2, voffA);
;             PG8_WAIT_V(8); PG8_WAIT_L(0); PG8_BAR; PG8_MMA(1, 0, At, B0); PG8_MMA(1, 1, At, B1); PG8_BAR; PG8_SCHED;
.LBB0_224:
	ds_read_b128 v[130:133], v219
	ds_read_b128 v[134:137], v219 offset:1024
	ds_read_b128 v[138:141], v219 offset:2048
	ds_read_b128 v[142:145], v219 offset:3072
	ds_read_b128 v[162:165], v220
	ds_read_b128 v[166:169], v220 offset:1024
	ds_read_b128 v[170:173], v220 offset:2048
	ds_read_b128 v[174:177], v220 offset:3072
	s_add_u32 s74, s10, 0xfff80080
	s_addc_u32 s75, s11, -1
	s_cmp_eq_u32 s63, 28
	s_cselect_b32 s75, s85, s75
	s_cselect_b32 s74, s84, s74
	s_cselect_b32 s77, s87, s61
	s_cselect_b32 s76, s86, s9
	v_lshl_add_u64 v[198:199], s[10:11], 0, v[154:155]
	s_add_i32 m0, s73, 0xc000
	ds_read_b128 v[178:181], v221
	ds_read_b128 v[182:185], v221 offset:1024
	ds_read_b128 v[186:189], v221 offset:2048
	ds_read_b128 v[190:193], v221 offset:3072
	ds_read_b128 v[194:197], v221 offset:4096
	ds_read_b128 v[224:227], v221 offset:5120
	ds_read_b128 v[228:231], v221 offset:6144
	ds_read_b128 v[232:235], v221 offset:7168
	global_load_lds_dwordx4 v[198:199], off
	v_lshl_add_u64 v[198:199], s[10:11], 0, v[158:159]
	s_add_i32 m0, s73, 0xe000
	s_nop 0
	global_load_lds_dwordx4 v[198:199], off
	s_waitcnt vmcnt(8)
	s_waitcnt lgkmcnt(0)
	s_barrier
	s_setprio 1
	s_waitcnt lgkmcnt(0)
	v_mfma_f32_16x16x32_bf16 v[126:129], v[130:133], v[178:181], v[126:129]
	v_mfma_f32_16x16x32_bf16 v[122:125], v[138:141], v[178:181], v[122:125]
	v_mfma_f32_16x16x32_bf16 v[110:113], v[130:133], v[186:189], v[110:113]
	v_mfma_f32_16x16x32_bf16 v[106:109], v[138:141], v[186:189], v[106:109]
	v_mfma_f32_16x16x32_bf16 v[94:97], v[130:133], v[194:197], v[94:97]
	v_mfma_f32_16x16x32_bf16 v[90:93], v[138:141], v[194:197], v[90:93]
	v_mfma_f32_16x16x32_bf16 v[78:81], v[130:133], v[228:231], v[78:81]
	v_mfma_f32_16x16x32_bf16 v[74:77], v[138:141], v[228:231], v[74:77]
	v_mfma_f32_16x16x32_bf16 v[126:129], v[134:137], v[182:185], v[126:129]
	v_mfma_f32_16x16x32_bf16 v[122:125], v[142:145], v[182:185], v[122:125]
	v_mfma_f32_16x16x32_bf16 v[110:113], v[134:137], v[190:193], v[110:113]
	v_mfma_f32_16x16x32_bf16 v[106:109], v[142:145], v[190:193], v[106:109]
	v_mfma_f32_16x16x32_bf16 v[94:97], v[134:137], v[224:227], v[94:97]
	v_mfma_f32_16x16x32_bf16 v[90:93], v[142:145], v[224:227], v[90:93]
	v_mfma_f32_16x16x32_bf16 v[78:81], v[134:137], v[232:235], v[78:81]
	v_mfma_f32_16x16x32_bf16 v[74:77], v[142:145], v[232:235], v[74:77]
	s_setprio 0
	s_setprio 1
	v_mfma_f32_16x16x32_bf16 v[118:121], v[162:165], v[178:181], v[118:121]
	v_mfma_f32_16x16x32_bf16 v[114:117], v[170:173], v[178:181], v[114:117]
	v_mfma_f32_16x16x32_bf16 v[102:105], v[162:165], v[186:189], v[102:105]
	v_mfma_f32_16x16x32_bf16 v[98:101], v[170:173], v[186:189], v[98:101]
	v_mfma_f32_16x16x32_bf16 v[86:89], v[162:165], v[194:197], v[86:89]
	v_mfma_f32_16x16x32_bf16 v[82:85], v[170:173], v[194:197], v[82:85]
	v_mfma_f32_16x16x32_bf16 v[70:73], v[162:165], v[228:231], v[70:73]
	v_mfma_f32_16x16x32_bf16 v[66:69], v[170:173], v[228:231], v[66:69]
	v_mfma_f32_16x16x32_bf16 v[118:121], v[166:169], v[182:185], v[118:121]
	v_mfma_f32_16x16x32_bf16 v[114:117], v[174:177], v[182:185], v[114:117]
	v_mfma_f32_16x16x32_bf16 v[102:105], v[166:169], v[190:193], v[102:105]
	v_mfma_f32_16x16x32_bf16 v[98:101], v[174:177], v[190:193], v[98:101]
	v_mfma_f32_16x16x32_bf16 v[86:89], v[166:169], v[224:227], v[86:89]
	v_mfma_f32_16x16x32_bf16 v[82:85], v[174:177], v[224:227], v[82:85]
	v_mfma_f32_16x16x32_bf16 v[70:73], v[166:169], v[232:235], v[70:73]
	v_mfma_f32_16x16x32_bf16 v[66:69], v[174:177], v[232:235], v[66:69]
	s_setprio 0
	s_barrier
	s_add_i32 s88, s57, s72
	v_lshl_add_u64 v[198:199], s[76:77], 0, v[146:147]
	s_mov_b32 m0, s88
	ds_read_b128 v[178:181], v221 offset:16384
	ds_read_b128 v[182:185], v221 offset:17408
	ds_read_b128 v[186:189], v221 offset:18432
	ds_read_b128 v[190:193], v221 offset:19456
	ds_read_b128 v[194:197], v221 offset:20480
	ds_read_b128 v[224:227], v221 offset:21504
	ds_read_b128 v[228:231], v221 offset:22528
	ds_read_b128 v[232:235], v221 offset:23552
	global_load_lds_dwordx4 v[198:199], off
	s_add_i32 m0, s88, 0x2000
	s_add_u32 s88, s76, 0x80000
	v_lshl_add_u64 v[236:237], s[76:77], 0, v[152:153]
	s_addc_u32 s89, s77, 0
	s_add_i32 s91, s59, s72
	global_load_lds_dwordx4 v[236:237], off
	v_lshl_add_u64 v[238:239], s[88:89], 0, v[146:147]
	s_mov_b32 m0, s91
	v_lshl_add_u64 v[240:241], s[74:75], 0, v[150:151]
	global_load_lds_dwordx4 v[238:239], off
	v_lshl_add_u64 v[238:239], s[88:89], 0, v[152:153]
	s_add_i32 m0, s91, 0x2000
	s_nop 0
	global_load_lds_dwordx4 v[238:239], off
	v_lshl_add_u64 v[238:239], s[74:75], 0, v[148:149]
	s_mov_b32 m0, s73
	s_nop 0
	global_load_lds_dwordx4 v[238:239], off
	s_mov_b32 m0, s33
	s_nop 0
	global_load_lds_dwordx4 v[240:241], off
	s_waitcnt vmcnt(8)
	s_waitcnt lgkmcnt(0)
	s_barrier
; #define PG8_STAGE(bufoff, gbase, voff) do { _Pragma("unroll") for (int _i = 0; _i < 2; ++_i) \
;         __builtin_amdgcn_global_load_lds((const unsigned*)((const char*)(gbase) + (voff)[_i]), (LAS unsigned*)(lds + (bufoff) + ldsw + _i * 8192), 16, 0, 0); } while (0)
; #define PG8_LDA(dst, b, h) do { _Pragma("unroll") for (int m = 0; m < 4; ++m) _Pragma("unroll") for (int k = 0; k < 2; ++k) dst[m][k] = *(const LAS bf16x8*)(lds + PG8_SA(b, h) + aoff + m * 2048 + k * 1024); } while (0)
; #define PG8_LDB(dst, b, h) do { _Pragma("unroll") for (int n = 0; n < 2; ++n) _Pragma("unroll") for (int k = 0; k < 2; ++k) dst[n][k] = *(const LAS bf16x8*)(lds + PG8_SB(b, h) + boff + n * 2048 + k * 1024); } while (0)
; #define PG8_MMA(ai, bj, At, Bt) do { __builtin_amdgcn_s_setprio(1); _Pragma("unroll") for (int m = 0; m < 4; ++m) _Pragma("unroll") for (int n = 0; n < 2; ++n) _Pragma("unroll") for (int k = 0; k < 2; ++k) \
;         acc[ai][bj][m][n] = __builtin_amdgcn_mfma_f32_16x16x32_bf16(Bt[n][k], At[m][k], acc[ai][bj][m][n], 0, 0, 0); __builtin_amdgcn_s_setprio(0); } while (0)
; #define PG8_WAIT_V(n) asm volatile("s_waitcnt vmcnt(" #n ")" ::: "memory")
; #define PG8_WAIT_L(n) asm volatile("s_waitcnt lgkmcnt(" #n ")" ::: "memory")
; #define PG8_BAR __builtin_amdgcn_s_barrier()
; #define PG8_SCHED __builtin_amdgcn_sched_barrier(0)
; #define PG8_STAGE(bufoff, gbase, voff) do { _Pragma("unroll") for (int _i = 0; _i < 2; ++_i) \
;         __builtin_amdgcn_global_load_lds((const unsigned*)((const char*)(gbase) + (voff)[_i]), (LAS unsigned*)(lds + (bufoff) + ldsw + _i * 8192), 16, 0, 0); } while (0)
; #define PG8_LDA(dst, b, h) do { _Pragma("unroll") for (int m = 0; m < 4; ++m) dst[m] = PG8_LD32(lds + PG8_SA(b, h) + aoff + m * 2048); } while (0)
; #define PG8_WAIT_V(n) asm volatile("s_waitcnt vmcnt(" #n ")" ::: "memory")
; template <class Epi, class Sched, bool ALIGN_EPI, bool SP2>
; __device__ __forceinline__ void gemm_phase(LAS unsigned char* lds, const int K, const Sched& S, const Epi& E) {
;     ...
;             PG8_WAIT_V(8); PG8_WAIT_L(0); PG8_BAR; PG8_MMA(1, 0, At, B0); PG8_MMA(1, 1, At, B1); PG8_BAR; PG8_SCHED;
;             PG8_LDB(B0, 1, 0); PG8_LDB(B1, 1, 1); PG8_SCHED; PG8_LDA(At, 1, 0); PG8_STAGE(PG8_SA(0, 1), a2 + hstep, voffA);
;             PG8_WAIT_V(8); PG8_WAIT_L(0); PG8_BAR; PG8_MMA(0, 0, At, B0); PG8_MMA(0, 1, At, B1); PG8_BAR; PG8_SCHED;
	s_setprio 1
	s_waitcnt lgkmcnt(0)
	v_mfma_f32_16x16x32_bf16 v[62:65], v[130:133], v[178:181], v[62:65]
	v_mfma_f32_16x16x32_bf16 v[58:61], v[138:141], v[178:181], v[58:61]
	v_mfma_f32_16x16x32_bf16 v[46:49], v[130:133], v[186:189], v[46:49]
	v_mfma_f32_16x16x32_bf16 v[42:45], v[138:141], v[186:189], v[42:45]
	v_mfma_f32_16x16x32_bf16 v[30:33], v[130:133], v[194:197], v[30:33]
	v_mfma_f32_16x16x32_bf16 v[26:29], v[138:141], v[194:197], v[26:29]
	v_mfma_f32_16x16x32_bf16 v[14:17], v[130:133], v[228:231], v[14:17]
	v_mfma_f32_16x16x32_bf16 v[10:13], v[138:141], v[228:231], v[10:13]
	v_mfma_f32_16x16x32_bf16 v[62:65], v[134:137], v[182:185], v[62:65]
	v_mfma_f32_16x16x32_bf16 v[58:61], v[142:145], v[182:185], v[58:61]
	v_mfma_f32_16x16x32_bf16 v[46:49], v[134:137], v[190:193], v[46:49]
	v_mfma_f32_16x16x32_bf16 v[42:45], v[142:145], v[190:193], v[42:45]
	v_mfma_f32_16x16x32_bf16 v[30:33], v[134:137], v[224:227], v[30:33]
	v_mfma_f32_16x16x32_bf16 v[26:29], v[142:145], v[224:227], v[26:29]
	v_mfma_f32_16x16x32_bf16 v[14:17], v[134:137], v[232:235], v[14:17]
	v_mfma_f32_16x16x32_bf16 v[10:13], v[142:145], v[232:235], v[10:13]
	s_setprio 0
	s_setprio 1
	v_mfma_f32_16x16x32_bf16 v[54:57], v[162:165], v[178:181], v[54:57]
	v_mfma_f32_16x16x32_bf16 v[50:53], v[170:173], v[178:181], v[50:53]
	v_mfma_f32_16x16x32_bf16 v[38:41], v[162:165], v[186:189], v[38:41]
	v_mfma_f32_16x16x32_bf16 v[34:37], v[170:173], v[186:189], v[34:37]
	v_mfma_f32_16x16x32_bf16 v[22:25], v[162:165], v[194:197], v[22:25]
	v_mfma_f32_16x16x32_bf16 v[18:21], v[170:173], v[194:197], v[18:21]
	v_mfma_f32_16x16x32_bf16 v[6:9], v[162:165], v[228:231], v[6:9]
	v_mfma_f32_16x16x32_bf16 v[2:5], v[170:173], v[228:231], v[2:5]
	v_mfma_f32_16x16x32_bf16 v[54:57], v[166:169], v[182:185], v[54:57]
	v_mfma_f32_16x16x32_bf16 v[50:53], v[174:177], v[182:185], v[50:53]
	v_mfma_f32_16x16x32_bf16 v[38:41], v[166:169], v[190:193], v[38:41]
	v_mfma_f32_16x16x32_bf16 v[34:37], v[174:177], v[190:193], v[34:37]
	v_mfma_f32_16x16x32_bf16 v[22:25], v[166:169], v[224:227], v[22:25]
	v_mfma_f32_16x16x32_bf16 v[18:21], v[174:177], v[224:227], v[18:21]
	v_mfma_f32_16x16x32_bf16 v[6:9], v[166:169], v[232:235], v[6:9]
	v_mfma_f32_16x16x32_bf16 v[2:5], v[174:177], v[232:235], v[2:5]
	s_setprio 0
	s_barrier
	s_add_i32 s88, 0, 0x18000
	s_add_i32 s89, 0, 0x1c000
	v_add_u32_e32 v142, s88, v216
	v_add_u32_e32 v156, s89, v216
	ds_read_b128 v[130:133], v142
	ds_read_b128 v[134:137], v142 offset:1024
	ds_read_b128 v[138:141], v142 offset:2048
	ds_read_b128 v[142:145], v142 offset:3072
	ds_read_b128 v[162:165], v156
	ds_read_b128 v[166:169], v156 offset:1024
	ds_read_b128 v[170:173], v156 offset:2048
	ds_read_b128 v[174:177], v156 offset:3072
	s_add_u32 s74, s74, 0x80000
	s_addc_u32 s75, s75, 0
	s_mov_b32 m0, s18
	v_lshl_add_u64 v[242:243], s[74:75], 0, v[148:149]
	ds_read_b128 v[178:181], v221 offset:32768
	ds_read_b128 v[182:185], v221 offset:33792
	ds_read_b128 v[186:189], v221 offset:34816
	ds_read_b128 v[190:193], v221 offset:35840
	ds_read_b128 v[194:197], v221 offset:36864
	ds_read_b128 v[224:227], v221 offset:37888
	ds_read_b128 v[228:231], v221 offset:38912
	ds_read_b128 v[232:235], v221 offset:39936
	global_load_lds_dwordx4 v[242:243], off
	v_lshl_add_u64 v[242:243], s[74:75], 0, v[150:151]
	s_mov_b32 m0, s19
	s_nop 0
	global_load_lds_dwordx4 v[242:243], off
	s_waitcnt vmcnt(8)
	s_waitcnt lgkmcnt(0)
	s_barrier
	s_setprio 1
	s_waitcnt lgkmcnt(0)
	v_mfma_f32_16x16x32_bf16 v[126:129], v[130:133], v[178:181], v[126:129]
	v_mfma_f32_16x16x32_bf16 v[122:125], v[138:141], v[178:181], v[122:125]
	v_mfma_f32_16x16x32_bf16 v[110:113], v[130:133], v[186:189], v[110:113]
	v_mfma_f32_16x16x32_bf16 v[106:109], v[138:141], v[186:189], v[106:109]
	v_mfma_f32_16x16x32_bf16 v[94:97], v[130:133], v[194:197], v[94:97]
	v_mfma_f32_16x16x32_bf16 v[90:93], v[138:141], v[194:197], v[90:93]
	v_mfma_f32_16x16x32_bf16 v[78:81], v[130:133], v[228:231], v[78:81]
	v_mfma_f32_16x16x32_bf16 v[74:77], v[138:141], v[228:231], v[74:77]
	v_mfma_f32_16x16x32_bf16 v[126:129], v[134:137], v[182:185], v[126:129]
	v_mfma_f32_16x16x32_bf16 v[122:125], v[142:145], v[182:185], v[122:125]
	v_mfma_f32_16x16x32_bf16 v[110:113], v[134:137], v[190:193], v[110:113]
	v_mfma_f32_16x16x32_bf16 v[106:109], v[142:145], v[190:193], v[106:109]
	v_mfma_f32_16x16x32_bf16 v[94:97], v[134:137], v[224:227], v[94:97]
	v_mfma_f32_16x16x32_bf16 v[90:93], v[142:145], v[224:227], v[90:93]
	v_mfma_f32_16x16x32_bf16 v[78:81], v[134:137], v[232:235], v[78:81]
	v_mfma_f32_16x16x32_bf16 v[74:77], v[142:145], v[232:235], v[74:77]
	s_setprio 0
	s_setprio 1
	v_mfma_f32_16x16x32_bf16 v[118:121], v[162:165], v[178:181], v[118:121]
	v_mfma_f32_16x16x32_bf16 v[114:117], v[170:173], v[178:181], v[114:117]
	v_mfma_f32_16x16x32_bf16 v[102:105], v[162:165], v[186:189], v[102:105]
	v_mfma_f32_16x16x32_bf16 v[98:101], v[170:173], v[186:189], v[98:101]
	v_mfma_f32_16x16x32_bf16 v[86:89], v[162:165], v[194:197], v[86:89]
	v_mfma_f32_16x16x32_bf16 v[82:85], v[170:173], v[194:197], v[82:85]
	v_mfma_f32_16x16x32_bf16 v[70:73], v[162:165], v[228:231], v[70:73]
	v_mfma_f32_16x16x32_bf16 v[66:69], v[170:173], v[228:231], v[66:69]
	v_mfma_f32_16x16x32_bf16 v[118:121], v[166:169], v[182:185], v[118:121]
	v_mfma_f32_16x16x32_bf16 v[114:117], v[174:177], v[182:185], v[114:117]
	v_mfma_f32_16x16x32_bf16 v[102:105], v[166:169], v[190:193], v[102:105]
	v_mfma_f32_16x16x32_bf16 v[98:101], v[174:177], v[190:193], v[98:101]
	v_mfma_f32_16x16x32_bf16 v[86:89], v[166:169], v[224:227], v[86:89]
	v_mfma_f32_16x16x32_bf16 v[82:85], v[174:177], v[224:227], v[82:85]
	v_mfma_f32_16x16x32_bf16 v[70:73], v[166:169], v[232:235], v[70:73]
	v_mfma_f32_16x16x32_bf16 v[66:69], v[174:177], v[232:235], v[66:69]
	s_setprio 0
	s_barrier
; #define PG8_STAGE(bufoff, gbase, voff) do { _Pragma("unroll") for (int _i = 0; _i < 2; ++_i) \
;         __builtin_amdgcn_global_load_lds((const unsigned*)((const char*)(gbase) + (voff)[_i]), (LAS unsigned*)(lds + (bufoff) + ldsw + _i * 8192), 16, 0, 0); } while (0)
; #define PG8_LDA(dst, b, h) do { _Pragma("unroll") for (int m = 0; m < 4; ++m) _Pragma("unroll") for (int k = 0; k < 2; ++k) dst[m][k] = *(const LAS bf16x8*)(lds + PG8_SA(b, h) + aoff + m * 2048 + k * 1024); } while (0)
; #define PG8_MMA(ai, bj, At, Bt) do { __builtin_amdgcn_s_setprio(1); _Pragma("unroll") for (int m = 0; m < 4; ++m) _Pragma("unroll") for (int n = 0; n < 2; ++n) _Pragma("unroll") for (int k = 0; k < 2; ++k) \
;         acc[ai][bj][m][n] = __builtin_amdgcn_mfma_f32_16x16x32_bf16(Bt[n][k], At[m][k], acc[ai][bj][m][n], 0, 0, 0); __builtin_amdgcn_s_setprio(0); } while (0)
; #define PG8_WAIT_V(n) asm volatile("s_waitcnt vmcnt(" #n ")" ::: "memory")
; #define PG8_WAIT_L(n) asm volatile("s_waitcnt lgkmcnt(" #n ")" ::: "memory")
; #define PG8_BAR __builtin_amdgcn_s_barrier()
; #define PG8_SCHED __builtin_amdgcn_sched_barrier(0)
; #define PG8_STAGE(bufoff, gbase, voff) do { _Pragma("unroll") for (int _i = 0; _i < 2; ++_i) \
;         __builtin_amdgcn_global_load_lds((const unsigned*)((const char*)(gbase) + (voff)[_i]), (LAS unsigned*)(lds + (bufoff) + ldsw + _i * 8192), 16, 0, 0); } while (0)
; #define PG8_LDA(dst, b, h) do { _Pragma("unroll") for (int m = 0; m < 4; ++m) dst[m] = PG8_LD32(lds + PG8_SA(b, h) + aoff + m * 2048); } while (0)
; #define PG8_BAR __builtin_amdgcn_s_barrier()
; template <class Epi, class Sched, bool ALIGN_EPI, bool SP2>
; __device__ __forceinline__ void gemm_phase(LAS unsigned char* lds, const int K, const Sched& S, const Epi& E) {
;     ...
;         for (int t = 0; t < nt; t += 2) {
;             const bool last = (t == nt - 2);
;             const char* a1 = cA + (size_t)(t + 1) * kstep;
;             const char* a2 = last ? nA : cA + (size_t)(t + 2) * kstep; const char* b2 = last ? nB : cB + (size_t)(t + 2) * kstep;
;             const char* a3 = a2 + kstep; const char* b3 = b2 + kstep;
;     ...
;             PG8_LDA(At, 1, 1); PG8_STAGE(PG8_SB(1, 0), b3, voffB); PG8_STAGE(PG8_SB(1, 1), b3 + hstep, voffB); PG8_STAGE(PG8_SA(1, 0), a3, voffA);
;             PG8_WAIT_V(8); PG8_WAIT_L(0); PG8_BAR; PG8_MMA(1, 0, At, B0); PG8_MMA(1, 1, At, B1); PG8_BAR; PG8_SCHED;
	s_add_i32 s74, s88, s72
	v_lshl_add_u64 v[198:199], v[198:199], 0, s[38:39]
	s_mov_b32 m0, s74
	ds_read_b128 v[178:181], v221 offset:49152
	ds_read_b128 v[182:185], v221 offset:50176
	ds_read_b128 v[186:189], v221 offset:51200
	ds_read_b128 v[190:193], v221 offset:52224
	ds_read_b128 v[194:197], v221 offset:53248
	ds_read_b128 v[224:227], v221 offset:54272
	ds_read_b128 v[228:231], v221 offset:55296
	ds_read_b128 v[232:235], v221 offset:56320
	global_load_lds_dwordx4 v[198:199], off
	s_add_i32 m0, s74, 0x2000
	s_add_u32 s74, s76, 0x80080
	v_lshl_add_u64 v[198:199], v[236:237], 0, s[38:39]
	s_addc_u32 s75, s77, 0
	s_add_i32 s76, s89, s72
	global_load_lds_dwordx4 v[198:199], off
	v_lshl_add_u64 v[198:199], s[74:75], 0, v[146:147]
	s_mov_b32 m0, s76
	s_nop 0
	global_load_lds_dwordx4 v[198:199], off
	v_lshl_add_u64 v[198:199], s[74:75], 0, v[152:153]
	s_add_i32 m0, s76, 0x2000
	s_nop 0
	global_load_lds_dwordx4 v[198:199], off
	v_lshl_add_u64 v[198:199], v[238:239], 0, s[38:39]
	s_mov_b32 m0, s22
	s_nop 0
	global_load_lds_dwordx4 v[198:199], off
	v_lshl_add_u64 v[198:199], v[240:241], 0, s[38:39]
	s_mov_b32 m0, s23
	s_nop 0
	global_load_lds_dwordx4 v[198:199], off
	s_waitcnt vmcnt(8)
	s_waitcnt lgkmcnt(0)
	s_barrier
	s_setprio 1
	s_waitcnt lgkmcnt(0)
	v_mfma_f32_16x16x32_bf16 v[62:65], v[130:133], v[178:181], v[62:65]
	v_mfma_f32_16x16x32_bf16 v[58:61], v[138:141], v[178:181], v[58:61]
	v_mfma_f32_16x16x32_bf16 v[46:49], v[130:133], v[186:189], v[46:49]
	v_mfma_f32_16x16x32_bf16 v[42:45], v[138:141], v[186:189], v[42:45]
	v_mfma_f32_16x16x32_bf16 v[30:33], v[130:133], v[194:197], v[30:33]
	v_mfma_f32_16x16x32_bf16 v[26:29], v[138:141], v[194:197], v[26:29]
	v_mfma_f32_16x16x32_bf16 v[14:17], v[130:133], v[228:231], v[14:17]
	v_mfma_f32_16x16x32_bf16 v[10:13], v[138:141], v[228:231], v[10:13]
	v_mfma_f32_16x16x32_bf16 v[62:65], v[134:137], v[182:185], v[62:65]
	v_mfma_f32_16x16x32_bf16 v[58:61], v[142:145], v[182:185], v[58:61]
	v_mfma_f32_16x16x32_bf16 v[46:49], v[134:137], v[190:193], v[46:49]
	v_mfma_f32_16x16x32_bf16 v[42:45], v[142:145], v[190:193], v[42:45]
	v_mfma_f32_16x16x32_bf16 v[30:33], v[134:137], v[224:227], v[30:33]
	v_mfma_f32_16x16x32_bf16 v[26:29], v[142:145], v[224:227], v[26:29]
	v_mfma_f32_16x16x32_bf16 v[14:17], v[134:137], v[232:235], v[14:17]
	v_mfma_f32_16x16x32_bf16 v[10:13], v[142:145], v[232:235], v[10:13]
	s_setprio 0
	s_setprio 1
	v_mfma_f32_16x16x32_bf16 v[54:57], v[162:165], v[178:181], v[54:57]
	v_mfma_f32_16x16x32_bf16 v[50:53], v[170:173], v[178:181], v[50:53]
	v_mfma_f32_16x16x32_bf16 v[38:41], v[162:165], v[186:189], v[38:41]
	v_mfma_f32_16x16x32_bf16 v[34:37], v[170:173], v[186:189], v[34:37]
	v_mfma_f32_16x16x32_bf16 v[22:25], v[162:165], v[194:197], v[22:25]
	v_mfma_f32_16x16x32_bf16 v[18:21], v[170:173], v[194:197], v[18:21]
	v_mfma_f32_16x16x32_bf16 v[6:9], v[162:165], v[228:231], v[6:9]
	v_mfma_f32_16x16x32_bf16 v[2:5], v[170:173], v[228:231], v[2:5]
	v_mfma_f32_16x16x32_bf16 v[54:57], v[166:169], v[182:185], v[54:57]
	v_mfma_f32_16x16x32_bf16 v[50:53], v[174:177], v[182:185], v[50:53]
	v_mfma_f32_16x16x32_bf16 v[38:41], v[166:169], v[190:193], v[38:41]
	v_mfma_f32_16x16x32_bf16 v[34:37], v[174:177], v[190:193], v[34:37]
	v_mfma_f32_16x16x32_bf16 v[22:25], v[166:169], v[224:227], v[22:25]
	v_mfma_f32_16x16x32_bf16 v[18:21], v[174:177], v[224:227], v[18:21]
	v_mfma_f32_16x16x32_bf16 v[6:9], v[166:169], v[232:235], v[6:9]
	v_mfma_f32_16x16x32_bf16 v[2:5], v[174:177], v[232:235], v[2:5]
	s_setprio 0
	s_barrier
	s_add_i32 s63, s63, 2
	s_add_u32 s10, s10, 0x100
	s_addc_u32 s11, s11, 0
	s_add_u32 s9, s9, 0x100
	s_addc_u32 s61, s61, 0
	s_cmp_gt_u32 s63, 29
	s_cbranch_scc0 .LBB0_224
	s_and_b64 vcc, exec, s[42:43]
	s_cbranch_vccz .LBB0_227
	s_barrier
